# vp56 plus P8 K-loop: s_setprio 1 hoisted before the pre-MFMA barrier and the redundant post-barrier lgkmcnt(0) wait dropped (byte-neutral)
# baseline (speedup 1.0000x reference)
.LBB0_723:
	ds_read_b128 v[154:157], v149
	ds_read_b128 v[158:161], v149 offset:1024
	ds_read_b128 v[162:165], v149 offset:2048
	ds_read_b128 v[166:169], v149 offset:3072
	ds_read_b128 v[170:173], v150
	ds_read_b128 v[174:177], v150 offset:1024
	ds_read_b128 v[178:181], v150 offset:2048
	ds_read_b128 v[182:185], v150 offset:3072
	s_add_u32 s30, s28, 0xfff80080
	s_addc_u32 s31, s29, -1
	s_cmp_eq_u32 s59, 28
	s_cselect_b32 s35, s1, s31
	s_cselect_b32 s34, s9, s30
	s_cselect_b32 s31, s19, s33
	s_cselect_b32 s30, s21, s27
	v_lshl_add_u64 v[144:145], s[28:29], 0, v[136:137]
	s_add_i32 m0, s47, 0xc000
	ds_read_b128 v[186:189], v151
	ds_read_b128 v[190:193], v151 offset:1024
	ds_read_b128 v[194:197], v151 offset:2048
	ds_read_b128 v[198:201], v151 offset:3072
	ds_read_b128 v[202:205], v151 offset:4096
	ds_read_b128 v[206:209], v151 offset:5120
	ds_read_b128 v[210:213], v151 offset:6144
	ds_read_b128 v[214:217], v151 offset:7168
	global_load_lds_dwordx4 v[144:145], off
	v_lshl_add_u64 v[144:145], s[28:29], 0, v[138:139]
	s_add_i32 m0, s47, 0xe000
	s_nop 0
	global_load_lds_dwordx4 v[144:145], off
	s_waitcnt vmcnt(8)
	s_waitcnt lgkmcnt(0)
	s_setprio 1
	s_nop 0
	s_barrier
	v_mfma_f32_16x16x32_bf16 v[124:127], v[154:157], v[186:189], v[124:127]
	v_mfma_f32_16x16x32_bf16 v[120:123], v[162:165], v[186:189], v[120:123]
	v_mfma_f32_16x16x32_bf16 v[108:111], v[154:157], v[194:197], v[108:111]
	v_mfma_f32_16x16x32_bf16 v[104:107], v[162:165], v[194:197], v[104:107]
	v_mfma_f32_16x16x32_bf16 v[92:95], v[154:157], v[202:205], v[92:95]
	v_mfma_f32_16x16x32_bf16 v[88:91], v[162:165], v[202:205], v[88:91]
	v_mfma_f32_16x16x32_bf16 v[76:79], v[154:157], v[210:213], v[76:79]
	v_mfma_f32_16x16x32_bf16 v[72:75], v[162:165], v[210:213], v[72:75]
	v_mfma_f32_16x16x32_bf16 v[124:127], v[158:161], v[190:193], v[124:127]
	v_mfma_f32_16x16x32_bf16 v[120:123], v[166:169], v[190:193], v[120:123]
	v_mfma_f32_16x16x32_bf16 v[108:111], v[158:161], v[198:201], v[108:111]
	v_mfma_f32_16x16x32_bf16 v[104:107], v[166:169], v[198:201], v[104:107]
	v_mfma_f32_16x16x32_bf16 v[92:95], v[158:161], v[206:209], v[92:95]
	v_mfma_f32_16x16x32_bf16 v[88:91], v[166:169], v[206:209], v[88:91]
	v_mfma_f32_16x16x32_bf16 v[76:79], v[158:161], v[214:217], v[76:79]
	v_mfma_f32_16x16x32_bf16 v[72:75], v[166:169], v[214:217], v[72:75]
	s_setprio 0
	s_setprio 1
	v_mfma_f32_16x16x32_bf16 v[116:119], v[170:173], v[186:189], v[116:119]
	v_mfma_f32_16x16x32_bf16 v[112:115], v[178:181], v[186:189], v[112:115]
	v_mfma_f32_16x16x32_bf16 v[100:103], v[170:173], v[194:197], v[100:103]
	v_mfma_f32_16x16x32_bf16 v[96:99], v[178:181], v[194:197], v[96:99]
	v_mfma_f32_16x16x32_bf16 v[84:87], v[170:173], v[202:205], v[84:87]
	v_mfma_f32_16x16x32_bf16 v[80:83], v[178:181], v[202:205], v[80:83]
	v_mfma_f32_16x16x32_bf16 v[68:71], v[170:173], v[210:213], v[68:71]
	v_mfma_f32_16x16x32_bf16 v[64:67], v[178:181], v[210:213], v[64:67]
	v_mfma_f32_16x16x32_bf16 v[116:119], v[174:177], v[190:193], v[116:119]
	v_mfma_f32_16x16x32_bf16 v[112:115], v[182:185], v[190:193], v[112:115]
	v_mfma_f32_16x16x32_bf16 v[100:103], v[174:177], v[198:201], v[100:103]
	v_mfma_f32_16x16x32_bf16 v[96:99], v[182:185], v[198:201], v[96:99]
	v_mfma_f32_16x16x32_bf16 v[84:87], v[174:177], v[206:209], v[84:87]
	v_mfma_f32_16x16x32_bf16 v[80:83], v[182:185], v[206:209], v[80:83]
	v_mfma_f32_16x16x32_bf16 v[68:71], v[174:177], v[214:217], v[68:71]
	v_mfma_f32_16x16x32_bf16 v[64:67], v[182:185], v[214:217], v[64:67]
	s_setprio 0
	s_barrier
	s_add_i32 s60, s56, s46
	v_lshl_add_u64 v[144:145], s[30:31], 0, v[130:131]
	s_mov_b32 m0, s60
	ds_read_b128 v[186:189], v151 offset:16384
	ds_read_b128 v[190:193], v151 offset:17408
	ds_read_b128 v[194:197], v151 offset:18432
	ds_read_b128 v[198:201], v151 offset:19456
	ds_read_b128 v[202:205], v151 offset:20480
	ds_read_b128 v[206:209], v151 offset:21504
	ds_read_b128 v[210:213], v151 offset:22528
	ds_read_b128 v[214:217], v151 offset:23552
	global_load_lds_dwordx4 v[144:145], off
	s_add_i32 m0, s60, 0x2000
	s_add_u32 s60, s30, 0x80000
	v_lshl_add_u64 v[218:219], s[30:31], 0, v[134:135]
	s_addc_u32 s61, s31, 0
	s_add_i32 s62, s57, s46
	global_load_lds_dwordx4 v[218:219], off
	v_lshl_add_u64 v[220:221], s[60:61], 0, v[130:131]
	s_mov_b32 m0, s62
	v_lshl_add_u64 v[222:223], s[34:35], 0, v[132:133]
	global_load_lds_dwordx4 v[220:221], off
	v_lshl_add_u64 v[220:221], s[60:61], 0, v[134:135]
	s_add_i32 m0, s62, 0x2000
	s_nop 0
	global_load_lds_dwordx4 v[220:221], off
	v_lshl_add_u64 v[220:221], s[34:35], 0, v[128:129]
	s_mov_b32 m0, s47
	s_nop 0
	global_load_lds_dwordx4 v[220:221], off
	s_mov_b32 m0, s36
	s_nop 0
	global_load_lds_dwordx4 v[222:223], off
	s_waitcnt vmcnt(8)
	s_waitcnt lgkmcnt(0)
	s_setprio 1
	s_nop 0
	s_barrier
	v_mfma_f32_16x16x32_bf16 v[60:63], v[154:157], v[186:189], v[60:63]
	v_mfma_f32_16x16x32_bf16 v[56:59], v[162:165], v[186:189], v[56:59]
	v_mfma_f32_16x16x32_bf16 v[44:47], v[154:157], v[194:197], v[44:47]
	v_mfma_f32_16x16x32_bf16 v[40:43], v[162:165], v[194:197], v[40:43]
	v_mfma_f32_16x16x32_bf16 v[28:31], v[154:157], v[202:205], v[28:31]
	v_mfma_f32_16x16x32_bf16 v[24:27], v[162:165], v[202:205], v[24:27]
	v_mfma_f32_16x16x32_bf16 v[12:15], v[154:157], v[210:213], v[12:15]
	v_mfma_f32_16x16x32_bf16 v[8:11], v[162:165], v[210:213], v[8:11]
	v_mfma_f32_16x16x32_bf16 v[60:63], v[158:161], v[190:193], v[60:63]
	v_mfma_f32_16x16x32_bf16 v[56:59], v[166:169], v[190:193], v[56:59]
	v_mfma_f32_16x16x32_bf16 v[44:47], v[158:161], v[198:201], v[44:47]
	v_mfma_f32_16x16x32_bf16 v[40:43], v[166:169], v[198:201], v[40:43]
	v_mfma_f32_16x16x32_bf16 v[28:31], v[158:161], v[206:209], v[28:31]
	v_mfma_f32_16x16x32_bf16 v[24:27], v[166:169], v[206:209], v[24:27]
	v_mfma_f32_16x16x32_bf16 v[12:15], v[158:161], v[214:217], v[12:15]
	v_mfma_f32_16x16x32_bf16 v[8:11], v[166:169], v[214:217], v[8:11]
	s_setprio 0
	s_setprio 1
	v_mfma_f32_16x16x32_bf16 v[52:55], v[170:173], v[186:189], v[52:55]
	v_mfma_f32_16x16x32_bf16 v[48:51], v[178:181], v[186:189], v[48:51]
	v_mfma_f32_16x16x32_bf16 v[36:39], v[170:173], v[194:197], v[36:39]
	v_mfma_f32_16x16x32_bf16 v[32:35], v[178:181], v[194:197], v[32:35]
	v_mfma_f32_16x16x32_bf16 v[20:23], v[170:173], v[202:205], v[20:23]
	v_mfma_f32_16x16x32_bf16 v[16:19], v[178:181], v[202:205], v[16:19]
	v_mfma_f32_16x16x32_bf16 v[4:7], v[170:173], v[210:213], v[4:7]
	v_mfma_f32_16x16x32_bf16 v[0:3], v[178:181], v[210:213], v[0:3]
	v_mfma_f32_16x16x32_bf16 v[52:55], v[174:177], v[190:193], v[52:55]
	v_mfma_f32_16x16x32_bf16 v[48:51], v[182:185], v[190:193], v[48:51]
	v_mfma_f32_16x16x32_bf16 v[36:39], v[174:177], v[198:201], v[36:39]
	v_mfma_f32_16x16x32_bf16 v[32:35], v[182:185], v[198:201], v[32:35]
	v_mfma_f32_16x16x32_bf16 v[20:23], v[174:177], v[206:209], v[20:23]
	v_mfma_f32_16x16x32_bf16 v[16:19], v[182:185], v[206:209], v[16:19]
	v_mfma_f32_16x16x32_bf16 v[4:7], v[174:177], v[214:217], v[4:7]
	v_mfma_f32_16x16x32_bf16 v[0:3], v[182:185], v[214:217], v[0:3]
	s_setprio 0
	s_barrier
	s_add_i32 s60, 0, 0x18000
	v_add_u32_e32 v153, s60, v147
	s_add_i32 s61, 0, 0x1c000
	ds_read_b128 v[154:157], v153
	ds_read_b128 v[158:161], v153 offset:1024
	ds_read_b128 v[162:165], v153 offset:2048
	ds_read_b128 v[166:169], v153 offset:3072
	v_add_u32_e32 v153, s61, v147
	ds_read_b128 v[170:173], v153
	ds_read_b128 v[174:177], v153 offset:1024
	ds_read_b128 v[178:181], v153 offset:2048
	ds_read_b128 v[182:185], v153 offset:3072
	s_add_u32 s34, s34, 0x80000
	s_addc_u32 s35, s35, 0
	s_mov_b32 m0, s37
	v_lshl_add_u64 v[224:225], s[34:35], 0, v[128:129]
	ds_read_b128 v[186:189], v151 offset:32768
	ds_read_b128 v[190:193], v151 offset:33792
	ds_read_b128 v[194:197], v151 offset:34816
	ds_read_b128 v[198:201], v151 offset:35840
	ds_read_b128 v[202:205], v151 offset:36864
	ds_read_b128 v[206:209], v151 offset:37888
	ds_read_b128 v[210:213], v151 offset:38912
	ds_read_b128 v[214:217], v151 offset:39936
	global_load_lds_dwordx4 v[224:225], off
	v_lshl_add_u64 v[224:225], s[34:35], 0, v[132:133]
	s_mov_b32 m0, s48
	s_nop 0
	global_load_lds_dwordx4 v[224:225], off
	s_waitcnt vmcnt(8)
	s_waitcnt lgkmcnt(0)
	s_setprio 1
	s_nop 0
	s_barrier
	v_mfma_f32_16x16x32_bf16 v[124:127], v[154:157], v[186:189], v[124:127]
	v_mfma_f32_16x16x32_bf16 v[120:123], v[162:165], v[186:189], v[120:123]
	v_mfma_f32_16x16x32_bf16 v[108:111], v[154:157], v[194:197], v[108:111]
	v_mfma_f32_16x16x32_bf16 v[104:107], v[162:165], v[194:197], v[104:107]
	v_mfma_f32_16x16x32_bf16 v[92:95], v[154:157], v[202:205], v[92:95]
	v_mfma_f32_16x16x32_bf16 v[88:91], v[162:165], v[202:205], v[88:91]
	v_mfma_f32_16x16x32_bf16 v[76:79], v[154:157], v[210:213], v[76:79]
	v_mfma_f32_16x16x32_bf16 v[72:75], v[162:165], v[210:213], v[72:75]
	v_mfma_f32_16x16x32_bf16 v[124:127], v[158:161], v[190:193], v[124:127]
	v_mfma_f32_16x16x32_bf16 v[120:123], v[166:169], v[190:193], v[120:123]
	v_mfma_f32_16x16x32_bf16 v[108:111], v[158:161], v[198:201], v[108:111]
	v_mfma_f32_16x16x32_bf16 v[104:107], v[166:169], v[198:201], v[104:107]
	v_mfma_f32_16x16x32_bf16 v[92:95], v[158:161], v[206:209], v[92:95]
	v_mfma_f32_16x16x32_bf16 v[88:91], v[166:169], v[206:209], v[88:91]
	v_mfma_f32_16x16x32_bf16 v[76:79], v[158:161], v[214:217], v[76:79]
	v_mfma_f32_16x16x32_bf16 v[72:75], v[166:169], v[214:217], v[72:75]
	s_setprio 0
	s_setprio 1
	v_mfma_f32_16x16x32_bf16 v[116:119], v[170:173], v[186:189], v[116:119]
	v_mfma_f32_16x16x32_bf16 v[112:115], v[178:181], v[186:189], v[112:115]
	v_mfma_f32_16x16x32_bf16 v[100:103], v[170:173], v[194:197], v[100:103]
	v_mfma_f32_16x16x32_bf16 v[96:99], v[178:181], v[194:197], v[96:99]
	v_mfma_f32_16x16x32_bf16 v[84:87], v[170:173], v[202:205], v[84:87]
	v_mfma_f32_16x16x32_bf16 v[80:83], v[178:181], v[202:205], v[80:83]
	v_mfma_f32_16x16x32_bf16 v[68:71], v[170:173], v[210:213], v[68:71]
	v_mfma_f32_16x16x32_bf16 v[64:67], v[178:181], v[210:213], v[64:67]
	v_mfma_f32_16x16x32_bf16 v[116:119], v[174:177], v[190:193], v[116:119]
	v_mfma_f32_16x16x32_bf16 v[112:115], v[182:185], v[190:193], v[112:115]
	v_mfma_f32_16x16x32_bf16 v[100:103], v[174:177], v[198:201], v[100:103]
	v_mfma_f32_16x16x32_bf16 v[96:99], v[182:185], v[198:201], v[96:99]
	v_mfma_f32_16x16x32_bf16 v[84:87], v[174:177], v[206:209], v[84:87]
	v_mfma_f32_16x16x32_bf16 v[80:83], v[182:185], v[206:209], v[80:83]
	v_mfma_f32_16x16x32_bf16 v[68:71], v[174:177], v[214:217], v[68:71]
	v_mfma_f32_16x16x32_bf16 v[64:67], v[182:185], v[214:217], v[64:67]
	s_setprio 0
	s_barrier
; #define PG8_BAR __builtin_amdgcn_s_barrier()
; template <class Epi, class Sched, bool ALIGN_EPI = false, bool SP2 = false, bool FP8 = false, bool MIX8 = false>
; __device__ __forceinline__ void gemm_phase(PG8_LAS unsigned char* lds, const Gemm g, const Sched& S, const Epi& E) {
;     ...
;         if constexpr (ALIGN_EPI) { if (wr == 0) PG8_BAR; }
	s_add_i32 s34, s60, s46
	v_lshl_add_u64 v[144:145], v[144:145], 0, s[14:15]
	s_mov_b32 m0, s34
	ds_read_b128 v[186:189], v151 offset:49152
	ds_read_b128 v[190:193], v151 offset:50176
	ds_read_b128 v[194:197], v151 offset:51200
	ds_read_b128 v[198:201], v151 offset:52224
	ds_read_b128 v[202:205], v151 offset:53248
	ds_read_b128 v[206:209], v151 offset:54272
	ds_read_b128 v[210:213], v151 offset:55296
	ds_read_b128 v[214:217], v151 offset:56320
	global_load_lds_dwordx4 v[144:145], off
	s_add_i32 m0, s34, 0x2000
	s_add_u32 s30, s30, 0x80080
	v_lshl_add_u64 v[144:145], v[218:219], 0, s[14:15]
	s_addc_u32 s31, s31, 0
	s_add_i32 s34, s61, s46
	global_load_lds_dwordx4 v[144:145], off
	v_lshl_add_u64 v[144:145], s[30:31], 0, v[130:131]
	s_mov_b32 m0, s34
	s_nop 0
	global_load_lds_dwordx4 v[144:145], off
	v_lshl_add_u64 v[144:145], s[30:31], 0, v[134:135]
	s_add_i32 m0, s34, 0x2000
	s_nop 0
	global_load_lds_dwordx4 v[144:145], off
	v_lshl_add_u64 v[144:145], v[220:221], 0, s[14:15]
	s_mov_b32 m0, s50
	s_nop 0
	global_load_lds_dwordx4 v[144:145], off
	v_lshl_add_u64 v[144:145], v[222:223], 0, s[14:15]
	s_mov_b32 m0, s51
	s_nop 0
	global_load_lds_dwordx4 v[144:145], off
	s_waitcnt vmcnt(8)
	s_waitcnt lgkmcnt(0)
	s_setprio 1
	s_nop 0
	s_barrier
	v_mfma_f32_16x16x32_bf16 v[60:63], v[154:157], v[186:189], v[60:63]
	v_mfma_f32_16x16x32_bf16 v[56:59], v[162:165], v[186:189], v[56:59]
	v_mfma_f32_16x16x32_bf16 v[44:47], v[154:157], v[194:197], v[44:47]
	v_mfma_f32_16x16x32_bf16 v[40:43], v[162:165], v[194:197], v[40:43]
	v_mfma_f32_16x16x32_bf16 v[28:31], v[154:157], v[202:205], v[28:31]
	v_mfma_f32_16x16x32_bf16 v[24:27], v[162:165], v[202:205], v[24:27]
	v_mfma_f32_16x16x32_bf16 v[12:15], v[154:157], v[210:213], v[12:15]
	v_mfma_f32_16x16x32_bf16 v[8:11], v[162:165], v[210:213], v[8:11]
	v_mfma_f32_16x16x32_bf16 v[60:63], v[158:161], v[190:193], v[60:63]
	v_mfma_f32_16x16x32_bf16 v[56:59], v[166:169], v[190:193], v[56:59]
	v_mfma_f32_16x16x32_bf16 v[44:47], v[158:161], v[198:201], v[44:47]
	v_mfma_f32_16x16x32_bf16 v[40:43], v[166:169], v[198:201], v[40:43]
	v_mfma_f32_16x16x32_bf16 v[28:31], v[158:161], v[206:209], v[28:31]
	v_mfma_f32_16x16x32_bf16 v[24:27], v[166:169], v[206:209], v[24:27]
	v_mfma_f32_16x16x32_bf16 v[12:15], v[158:161], v[214:217], v[12:15]
	v_mfma_f32_16x16x32_bf16 v[8:11], v[166:169], v[214:217], v[8:11]
	s_setprio 0
	s_setprio 1
	v_mfma_f32_16x16x32_bf16 v[52:55], v[170:173], v[186:189], v[52:55]
	v_mfma_f32_16x16x32_bf16 v[48:51], v[178:181], v[186:189], v[48:51]
	v_mfma_f32_16x16x32_bf16 v[36:39], v[170:173], v[194:197], v[36:39]
	v_mfma_f32_16x16x32_bf16 v[32:35], v[178:181], v[194:197], v[32:35]
	v_mfma_f32_16x16x32_bf16 v[20:23], v[170:173], v[202:205], v[20:23]
	v_mfma_f32_16x16x32_bf16 v[16:19], v[178:181], v[202:205], v[16:19]
	v_mfma_f32_16x16x32_bf16 v[4:7], v[170:173], v[210:213], v[4:7]
	v_mfma_f32_16x16x32_bf16 v[0:3], v[178:181], v[210:213], v[0:3]
	v_mfma_f32_16x16x32_bf16 v[52:55], v[174:177], v[190:193], v[52:55]
	v_mfma_f32_16x16x32_bf16 v[48:51], v[182:185], v[190:193], v[48:51]
	v_mfma_f32_16x16x32_bf16 v[36:39], v[174:177], v[198:201], v[36:39]
	v_mfma_f32_16x16x32_bf16 v[32:35], v[182:185], v[198:201], v[32:35]
	v_mfma_f32_16x16x32_bf16 v[20:23], v[174:177], v[206:209], v[20:23]
	v_mfma_f32_16x16x32_bf16 v[16:19], v[182:185], v[206:209], v[16:19]
	v_mfma_f32_16x16x32_bf16 v[4:7], v[174:177], v[214:217], v[4:7]
	v_mfma_f32_16x16x32_bf16 v[0:3], v[182:185], v[214:217], v[0:3]
	s_setprio 0
	s_barrier
	s_add_i32 s59, s59, 2
	s_add_u32 s28, s28, 0x100
	s_addc_u32 s29, s29, 0
	s_add_u32 s27, s27, 0x100
	s_addc_u32 s33, s33, 0
	s_cmp_gt_u32 s59, 29
	s_cbranch_scc0 .LBB0_723
	s_and_b64 vcc, exec, s[16:17]
	s_cbranch_vccz .LBB0_726
	s_barrier
